# v75 plus J-phase layer-1 loop: LN gamma/beta chunks loaded once before the loop (were reloaded per row and chunk with a wait each)
# baseline (speedup 1.0000x reference)
.LBB0_1703:
	s_or_b64 exec, exec, s[10:11]
	v_mov_b32_e32 v1, v232
	s_mov_b64 s[8:9], s[46:47]
	s_mov_b64 s[12:13], s[0:1]
	v_mov_b32_e32 v6, v0
	s_mov_b64 s[10:11], s[44:45]
	s_waitcnt lgkmcnt(0)
	s_barrier
	s_mov_b64 s[10:11], -1
	v_readlane_b32 s8, v254, 49
	v_readlane_b32 s9, v254, 50
	s_and_b64 vcc, exec, s[8:9]
	s_cbranch_vccz .LBB0_1707
	v_readlane_b32 s8, v254, 45
	v_readlane_b32 s26, v254, 26
	v_readlane_b32 s9, v254, 46
	v_readlane_b32 s14, v254, 24
	v_readlane_b32 s16, v254, 14
	v_readlane_b32 s27, v254, 27
	v_readlane_b32 s34, v254, 16
	v_readlane_b32 s36, v254, 18
	s_and_b64 vcc, exec, s[8:9]
	v_readlane_b32 s15, v254, 25
	v_readlane_b32 s17, v254, 15
	v_readlane_b32 s8, v254, 20
	v_readlane_b32 s35, v254, 17
	v_readlane_b32 s37, v254, 19
	s_mov_b32 s27, 0x1d91e000
	s_movk_i32 s38, 0xf000
	s_mov_b64 s[54:55], 0x1d91e000
	v_readlane_b32 s9, v254, 21
	s_cbranch_vccnz .LBB0_1706
	s_load_dwordx4 s[76:79], s[0:1], 0xb0
	v_lshlrev_b32_e32 v90, 4, v232
	v_add_u32_e32 v91, 0x1000, v90
	s_waitcnt lgkmcnt(0)
	s_add_u32 s76, s76, 0x2000
	s_addc_u32 s77, s77, 0
	s_add_u32 s78, s78, 0x2000
	s_addc_u32 s79, s79, 0
	global_load_dwordx4 v[180:183], v90, s[76:77]
	global_load_dwordx4 v[212:215], v90, s[78:79]
	global_load_dwordx4 v[184:187], v90, s[76:77] offset:1024
	global_load_dwordx4 v[216:219], v90, s[78:79] offset:1024
	global_load_dwordx4 v[188:191], v90, s[76:77] offset:2048
	global_load_dwordx4 v[220:223], v90, s[78:79] offset:2048
	global_load_dwordx4 v[192:195], v90, s[76:77] offset:3072
	global_load_dwordx4 v[236:239], v90, s[78:79] offset:3072
	global_load_dwordx4 v[196:199], v91, s[76:77]
	global_load_dwordx4 v[240:243], v91, s[78:79]
	global_load_dwordx4 v[200:203], v91, s[76:77] offset:1024
	global_load_dwordx4 v[128:131], v91, s[78:79] offset:1024
	global_load_dwordx4 v[204:207], v91, s[76:77] offset:2048
	global_load_dwordx4 v[132:135], v91, s[78:79] offset:2048
	global_load_dwordx4 v[208:211], v91, s[76:77] offset:3072
	global_load_dwordx4 v[140:143], v91, s[78:79] offset:3072
.LBB0_1705:
	s_mov_b64 s[10:11], s[0:1]
	v_mov_b32_e32 v2, v0
	s_mov_b64 s[22:23], s[44:45]
	v_mov_b32_e32 v1, v232
	s_mov_b64 s[18:19], s[46:47]
	s_add_i32 s9, s60, s8
	v_lshlrev_b32_e32 v2, 2, v1
	v_ashrrev_i32_e32 v3, 31, v2
	v_lshlrev_b64 v[4:5], 1, v[2:3]
	v_lshl_add_u64 v[8:9], s[18:19], 0, v[4:5]
	v_lshl_add_u64 v[8:9], v[8:9], 0, s[16:17]
	global_load_dwordx2 v[56:57], v[8:9], off offset:-3584
	global_load_dwordx2 v[62:63], v[8:9], off offset:-3072
	global_load_dwordx2 v[66:67], v[8:9], off offset:-2560
	global_load_dwordx2 v[10:11], v[8:9], off offset:-2048
	s_cmpk_lt_i32 s9, 0x2000
	s_cselect_b32 s24, s9, s8
	s_ashr_i32 s25, s24, 31
	s_lshl_b64 s[20:21], s[24:25], 12
	s_add_u32 s18, s18, s20
	s_addc_u32 s19, s19, s21
	v_lshl_add_u64 v[4:5], s[18:19], 0, v[4:5]
	v_and_b32_e32 v7, 64, v249
	v_add_u32_e32 v12, 64, v7
	v_xor_b32_e32 v7, 1, v249
	s_waitcnt vmcnt(3)
	v_lshlrev_b32_e32 v68, 16, v56
	s_waitcnt vmcnt(2)
	v_lshlrev_b32_e32 v69, 16, v62
	v_and_b32_e32 v71, 0xffff0000, v62
	s_waitcnt vmcnt(0)
	v_lshlrev_b32_e32 v58, 16, v10
	v_and_b32_e32 v59, 0xffff0000, v10
	v_lshlrev_b32_e32 v60, 16, v11
	v_and_b32_e32 v61, 0xffff0000, v11
	global_load_dwordx2 v[10:11], v[8:9], off offset:-1536
	v_and_b32_e32 v70, 0xffff0000, v56
	v_lshlrev_b32_e32 v65, 16, v63
	v_lshlrev_b32_e32 v64, 16, v57
	v_and_b32_e32 v75, 0xffff0000, v63
	v_and_b32_e32 v74, 0xffff0000, v57
	v_pk_add_f32 v[56:57], v[64:65], v[74:75]
	v_lshlrev_b32_e32 v63, 16, v67
	v_lshlrev_b32_e32 v62, 16, v66
	v_and_b32_e32 v73, 0xffff0000, v67
	v_and_b32_e32 v72, 0xffff0000, v66
	v_add_f32_e32 v54, v58, v59
	v_add_f32_e32 v52, v60, v61
	s_waitcnt vmcnt(0)
	v_lshlrev_b32_e32 v51, 16, v10
	v_and_b32_e32 v49, 0xffff0000, v10
	v_lshlrev_b32_e32 v55, 16, v11
	v_and_b32_e32 v53, 0xffff0000, v11
	global_load_dwordx2 v[76:77], v[8:9], off offset:-1024
	global_load_dwordx2 v[10:11], v[8:9], off offset:-512
	s_waitcnt vmcnt(0)
	v_lshlrev_b32_e32 v46, 16, v11
	global_load_dwordx2 v[8:9], v[8:9], off
	v_and_b32_e32 v47, 0xffff0000, v11
	v_lshlrev_b32_e32 v40, 16, v10
	v_and_b32_e32 v41, 0xffff0000, v10
	v_add_f32_e32 v44, v40, v41
	v_add_f32_e32 v42, v46, v47
	s_waitcnt vmcnt(0)
	v_lshlrev_b32_e32 v38, 16, v8
	v_and_b32_e32 v39, 0xffff0000, v8
	v_lshlrev_b32_e32 v45, 16, v9
	v_and_b32_e32 v43, 0xffff0000, v9
	v_lshl_add_u64 v[8:9], v[4:5], 0, s[54:55]
	v_add_co_u32_e32 v4, vcc, s27, v4
	s_nop 1
	v_addc_co_u32_e32 v5, vcc, 0, v5, vcc
	global_load_dwordx2 v[34:35], v[4:5], off
	global_load_dwordx2 v[36:37], v[8:9], off offset:512
	global_load_dwordx2 v[32:33], v[8:9], off offset:1024
	s_nop 0
	global_load_dwordx2 v[4:5], v[8:9], off offset:1536
	v_cmp_lt_i32_e32 vcc, v7, v12
	s_waitcnt vmcnt(0)
	v_lshlrev_b32_e32 v26, 16, v4
	v_and_b32_e32 v27, 0xffff0000, v4
	v_lshlrev_b32_e32 v28, 16, v5
	v_and_b32_e32 v29, 0xffff0000, v5
	global_load_dwordx2 v[4:5], v[8:9], off offset:2048
	v_cndmask_b32_e32 v7, v249, v7, vcc
	v_lshlrev_b32_e32 v7, 2, v7
	v_add_f32_e32 v24, v26, v27
	s_waitcnt vmcnt(0)
	v_lshlrev_b32_e32 v21, 16, v4
	v_and_b32_e32 v19, 0xffff0000, v4
	v_lshlrev_b32_e32 v25, 16, v5
	v_and_b32_e32 v23, 0xffff0000, v5
	global_load_dwordx2 v[30:31], v[8:9], off offset:2560
	global_load_dwordx2 v[4:5], v[8:9], off offset:3072
	s_load_dwordx4 s[28:31], s[10:11], 0xb0
	s_waitcnt lgkmcnt(0)
	s_add_u32 s20, s28, 0x2000
	s_addc_u32 s21, s29, 0
	s_add_u32 s18, s30, 0x2000
	s_addc_u32 s19, s31, 0
	s_waitcnt vmcnt(0)
	v_lshlrev_b32_e32 v14, 16, v4
	v_and_b32_e32 v15, 0xffff0000, v4
	v_lshlrev_b32_e32 v16, 16, v5
	v_and_b32_e32 v17, 0xffff0000, v5
	global_load_dwordx2 v[4:5], v[8:9], off offset:3584
	s_waitcnt vmcnt(0)
	v_lshlrev_b32_e32 v8, 16, v4
	v_and_b32_e32 v9, 0xffff0000, v4
	v_lshlrev_b32_e32 v13, 16, v5
	v_and_b32_e32 v11, 0xffff0000, v5
	v_pk_add_f32 v[4:5], v[68:69], v[70:71]
	s_nop 0
	v_pk_add_f32 v[4:5], v[4:5], v[56:57]
	v_pk_add_f32 v[56:57], v[54:55], v[52:53]
	v_add_f32_e32 v4, 0, v4
	v_add_f32_e32 v50, v4, v5
	v_pk_add_f32 v[4:5], v[62:63], v[72:73]
	s_nop 0
	v_pk_add_f32 v[4:5], v[4:5], v[4:5] op_sel:[0,1] op_sel_hi:[1,0]
	s_nop 0
	v_mov_b32_e32 v5, v49
	v_pk_add_f32 v[4:5], v[50:51], v[4:5]
	s_nop 0
	v_pk_add_f32 v[66:67], v[4:5], v[56:57]
	v_lshlrev_b32_e32 v57, 16, v77
	v_lshlrev_b32_e32 v56, 16, v76
	v_and_b32_e32 v5, 0xffff0000, v77
	v_and_b32_e32 v4, 0xffff0000, v76
	v_pk_add_f32 v[76:77], v[56:57], v[4:5]
	v_pk_add_f32 v[66:67], v[66:67], v[66:67] op_sel:[0,1] op_sel_hi:[1,0]
	v_pk_add_f32 v[76:77], v[76:77], v[76:77] op_sel:[0,1] op_sel_hi:[1,0]
	v_mov_b32_e32 v67, v38
	v_mov_b32_e32 v77, v39
	v_pk_add_f32 v[66:67], v[66:67], v[76:77]
	v_pk_add_f32 v[76:77], v[44:45], v[42:43]
	v_lshlrev_b32_e32 v44, 16, v35
	v_pk_add_f32 v[66:67], v[66:67], v[76:77]
	s_nop 0
	v_add_f32_e32 v10, v66, v67
	ds_bpermute_b32 v18, v7, v10
	s_waitcnt lgkmcnt(0)
	v_add_f32_e32 v10, v10, v18
	v_xor_b32_e32 v18, 2, v249
	v_cmp_lt_i32_e32 vcc, v18, v12
	s_nop 1
	v_cndmask_b32_e32 v18, v249, v18, vcc
	v_lshlrev_b32_e32 v18, 2, v18
	ds_bpermute_b32 v20, v18, v10
	s_waitcnt lgkmcnt(0)
	v_add_f32_e32 v10, v10, v20
	v_xor_b32_e32 v20, 4, v249
	v_cmp_lt_i32_e32 vcc, v20, v12
	s_nop 1
	v_cndmask_b32_e32 v20, v249, v20, vcc
	v_lshlrev_b32_e32 v50, 2, v20
	ds_bpermute_b32 v20, v50, v10
	s_waitcnt lgkmcnt(0)
	v_add_f32_e32 v10, v10, v20
	v_xor_b32_e32 v20, 8, v249
	v_cmp_lt_i32_e32 vcc, v20, v12
	s_nop 1
	v_cndmask_b32_e32 v20, v249, v20, vcc
	v_lshlrev_b32_e32 v54, 2, v20
	ds_bpermute_b32 v20, v54, v10
	s_waitcnt lgkmcnt(0)
	v_add_f32_e32 v10, v10, v20
	v_xor_b32_e32 v20, 16, v249
	v_cmp_lt_i32_e32 vcc, v20, v12
	s_nop 1
	v_cndmask_b32_e32 v20, v249, v20, vcc
	v_lshlrev_b32_e32 v82, 2, v20
	ds_bpermute_b32 v20, v82, v10
	s_waitcnt lgkmcnt(0)
	v_add_f32_e32 v10, v10, v20
	v_xor_b32_e32 v20, 32, v249
	v_cmp_lt_i32_e32 vcc, v20, v12
	s_nop 1
	v_cndmask_b32_e32 v12, v249, v20, vcc
	v_lshlrev_b32_e32 v84, 2, v12
	ds_bpermute_b32 v12, v84, v10
	s_waitcnt lgkmcnt(0)
	v_add_f32_e32 v12, v10, v12
	v_fmac_f32_e32 v70, 0xba000000, v12
	v_fmac_f32_e32 v71, 0xba000000, v12
	v_fmac_f32_e32 v74, 0xba000000, v12
	v_fmac_f32_e32 v68, 0xba000000, v12
	v_fmac_f32_e32 v75, 0xba000000, v12
	v_fmac_f32_e32 v69, 0xba000000, v12
	v_mov_b32_e32 v67, v71
	v_mov_b32_e32 v79, v70
	v_pk_mul_f32 v[70:71], v[70:71], v[70:71]
	v_fmac_f32_e32 v64, 0xba000000, v12
	v_fmac_f32_e32 v65, 0xba000000, v12
	v_mov_b32_e32 v66, v69
	v_mov_b32_e32 v78, v68
	v_pk_fma_f32 v[68:69], v[68:69], v[68:69], v[70:71]
	v_mov_b32_e32 v71, v75
	v_mov_b32_e32 v81, v74
	v_pk_mul_f32 v[74:75], v[74:75], v[74:75]
	v_mov_b32_e32 v70, v65
	v_mov_b32_e32 v80, v64
	v_pk_fma_f32 v[64:65], v[64:65], v[64:65], v[74:75]
	v_fmac_f32_e32 v72, 0xba000000, v12
	v_fmac_f32_e32 v73, 0xba000000, v12
	v_fmac_f32_e32 v63, 0xba000000, v12
	v_pk_add_f32 v[64:65], v[68:69], v[64:65]
	v_fmac_f32_e32 v62, 0xba000000, v12
	v_mov_b32_e32 v68, v63
	v_mov_b32_e32 v69, v73
	v_mov_b32_e32 v63, v72
	v_pk_mul_f32 v[74:75], v[68:69], v[68:69]
	v_pk_mul_f32 v[72:73], v[62:63], v[62:63]
	v_fmac_f32_e32 v58, 0xba000000, v12
	v_pk_mov_b32 v[76:77], v[72:73], v[74:75] op_sel:[1,0]
	v_mov_b32_e32 v73, v75
	v_fmac_f32_e32 v59, 0xba000000, v12
	v_fmac_f32_e32 v60, 0xba000000, v12
	v_mul_f32_e32 v10, v58, v58
	v_pk_add_f32 v[72:73], v[76:77], v[72:73]
	v_fmac_f32_e32 v61, 0xba000000, v12
	v_pk_fma_f32 v[74:75], v[58:59], v[58:59], v[10:11] op_sel_hi:[1,1,0]
	v_mul_f32_e32 v10, v60, v60
	v_pk_add_f32 v[64:65], v[64:65], v[64:65] op_sel_hi:[0,1]
	v_pk_add_f32 v[72:73], v[72:73], v[72:73] op_sel_hi:[0,1]
	v_pk_fma_f32 v[76:77], v[60:61], v[60:61], v[10:11] op_sel_hi:[1,1,0]
	v_fmac_f32_e32 v53, 0xba000000, v12
	v_fmac_f32_e32 v55, 0xba000000, v12
	v_fmac_f32_e32 v49, 0xba000000, v12
	v_fmac_f32_e32 v51, 0xba000000, v12
	v_mul_f32_e32 v74, v51, v51
	v_mul_f32_e32 v76, v49, v49
	v_mul_f32_e32 v72, v55, v55
	v_mul_f32_e32 v64, v53, v53
	v_pk_add_f32 v[74:75], v[74:75], v[76:77]
	v_pk_add_f32 v[64:65], v[72:73], v[64:65]
	v_fmac_f32_e32 v4, 0xba000000, v12
	v_pk_add_f32 v[64:65], v[74:75], v[64:65]
	v_fmac_f32_e32 v5, 0xba000000, v12
	v_fmac_f32_e32 v57, 0xba000000, v12
	v_pk_add_f32 v[72:73], v[64:65], v[64:65] op_sel_hi:[0,1]
	v_fmac_f32_e32 v56, 0xba000000, v12
	v_mov_b32_e32 v64, v57
	v_mov_b32_e32 v65, v5
	v_mov_b32_e32 v57, v4
	v_pk_mul_f32 v[74:75], v[64:65], v[64:65]
	v_pk_mul_f32 v[4:5], v[56:57], v[56:57]
	v_fmac_f32_e32 v40, 0xba000000, v12
	v_pk_mov_b32 v[76:77], v[4:5], v[74:75] op_sel:[1,0]
	v_mov_b32_e32 v5, v75
	v_pk_add_f32 v[4:5], v[76:77], v[4:5]
	v_fmac_f32_e32 v41, 0xba000000, v12
	v_pk_add_f32 v[4:5], v[4:5], v[4:5] op_sel_hi:[0,1]
	v_fmac_f32_e32 v46, 0xba000000, v12
	v_mul_f32_e32 v4, v40, v40
	v_fmac_f32_e32 v47, 0xba000000, v12
	v_pk_fma_f32 v[74:75], v[40:41], v[40:41], v[4:5] op_sel_hi:[1,1,0]
	v_mul_f32_e32 v4, v46, v46
	v_pk_fma_f32 v[76:77], v[46:47], v[46:47], v[4:5] op_sel_hi:[1,1,0]
	v_fmac_f32_e32 v43, 0xba000000, v12
	v_fmac_f32_e32 v45, 0xba000000, v12
	v_fmac_f32_e32 v39, 0xba000000, v12
	v_fmac_f32_e32 v38, 0xba000000, v12
	v_mul_f32_e32 v74, v38, v38
	v_mul_f32_e32 v76, v39, v39
	v_mul_f32_e32 v4, v45, v45
	v_mul_f32_e32 v72, v43, v43
	v_pk_add_f32 v[74:75], v[74:75], v[76:77]
	v_pk_add_f32 v[4:5], v[4:5], v[72:73]
	v_lshlrev_b64 v[72:73], 2, v[2:3]
	v_pk_add_f32 v[4:5], v[74:75], v[4:5]
	v_lshl_add_u64 v[76:77], s[20:21], 0, v[72:73]
	v_add_f32_e32 v4, v4, v5
	ds_bpermute_b32 v5, v7, v4
	v_lshl_add_u64 v[74:75], s[18:19], 0, v[72:73]
	s_nop 1
	v_mov_b64_e32 v[86:87], v[212:213]
	v_mov_b64_e32 v[88:89], v[214:215]
	v_lshl_add_u64 v[72:73], s[22:23], 0, v[72:73]
	v_lshl_add_u64 v[72:73], v[72:73], 0, s[14:15]
	s_waitcnt lgkmcnt(0)
	v_add_f32_e32 v4, v4, v5
	ds_bpermute_b32 v5, v18, v4
	v_mov_b32_e32 v52, v55
	v_mov_b32_e32 v48, v51
	v_mov_b32_e32 v42, v45
	v_lshlrev_b32_e32 v45, 16, v37
	s_waitcnt lgkmcnt(0)
	v_add_f32_e32 v4, v4, v5
	ds_bpermute_b32 v5, v50, v4
	s_waitcnt lgkmcnt(0)
	v_add_f32_e32 v4, v4, v5
	ds_bpermute_b32 v5, v54, v4
	s_waitcnt lgkmcnt(0)
	v_add_f32_e32 v4, v4, v5
	ds_bpermute_b32 v5, v82, v4
	s_waitcnt lgkmcnt(0)
	v_add_f32_e32 v4, v4, v5
	ds_bpermute_b32 v5, v84, v4
	s_waitcnt lgkmcnt(0)
	v_add_f32_e32 v4, v4, v5
	v_fmamk_f32 v4, v4, 0x3a000000, v250
	v_cmp_gt_f32_e32 vcc, s96, v4
	v_mul_f32_e32 v5, 0x4f800000, v4
	s_nop 0
	v_cndmask_b32_e32 v4, v4, v5, vcc
	v_sqrt_f32_e32 v5, v4
	s_nop 0
	v_add_u32_e32 v10, -1, v5
	v_fma_f32 v12, -v10, v5, v4
	v_cmp_ge_f32_e64 s[10:11], 0, v12
	v_add_u32_e32 v12, 1, v5
	s_nop 0
	v_cndmask_b32_e64 v10, v5, v10, s[10:11]
	v_fma_f32 v5, -v12, v5, v4
	v_cmp_lt_f32_e64 s[10:11], 0, v5
	s_nop 1
	v_cndmask_b32_e64 v5, v10, v12, s[10:11]
	v_mul_f32_e32 v10, 0x37800000, v5
	v_cndmask_b32_e32 v5, v5, v10, vcc
	v_cmp_class_f32_e32 vcc, v4, v251
	s_nop 1
	v_cndmask_b32_e32 v4, v5, v4, vcc
	v_div_scale_f32 v5, s[10:11], v4, v4, 1.0
	v_rcp_f32_e32 v10, v5
	s_lshl_b64 s[10:11], s[24:25], 13
	s_add_u32 s22, s22, s10
	s_addc_u32 s23, s23, s11
	v_fma_f32 v12, -v5, v10, 1.0
	v_fmac_f32_e32 v10, v12, v10
	v_div_scale_f32 v12, vcc, 1.0, v4, 1.0
	v_mul_f32_e32 v20, v12, v10
	v_fma_f32 v22, -v5, v20, v12
	v_fmac_f32_e32 v20, v22, v10
	v_fma_f32 v5, -v5, v20, v12
	v_div_fmas_f32 v5, v5, v10, v20
	v_div_fixup_f32 v10, v5, v4, 1.0
	s_nop 1
	v_mov_b64_e32 v[2:3], v[180:181]
	v_mov_b64_e32 v[4:5], v[182:183]
	v_pk_mul_f32 v[78:79], v[78:79], v[10:11] op_sel_hi:[1,0]
	v_pk_mul_f32 v[80:81], v[80:81], v[10:11] op_sel_hi:[1,0]
	v_pk_mul_f32 v[70:71], v[70:71], v[10:11] op_sel_hi:[1,0]
	v_pk_mul_f32 v[66:67], v[66:67], v[10:11] op_sel_hi:[1,0]
	v_pk_mul_f32 v[62:63], v[62:63], v[10:11] op_sel_hi:[1,0]
	v_pk_mul_f32 v[60:61], v[60:61], v[10:11] op_sel_hi:[1,0]
	v_pk_mul_f32 v[58:59], v[58:59], v[10:11] op_sel_hi:[1,0]
	v_pk_mul_f32 v[52:53], v[52:53], v[10:11] op_sel_hi:[1,0]
	v_pk_mul_f32 v[48:49], v[48:49], v[10:11] op_sel_hi:[1,0]
	v_pk_mul_f32 v[46:47], v[46:47], v[10:11] op_sel_hi:[1,0]
	v_pk_mul_f32 v[40:41], v[40:41], v[10:11] op_sel_hi:[1,0]
	v_pk_mul_f32 v[38:39], v[38:39], v[10:11] op_sel_hi:[1,0]
	v_add_f32_e32 v22, v28, v29
	v_add_f32_e32 v12, v14, v15
	s_add_i32 s8, s8, s26
	s_add_u32 s16, s16, s34
	s_addc_u32 s17, s17, s35
	s_add_u32 s14, s14, s36
	s_addc_u32 s15, s15, s37
	s_cmpk_lt_i32 s8, 0x2000
	s_waitcnt vmcnt(0)
	v_pk_fma_f32 v[2:3], v[2:3], v[78:79], v[86:87]
	v_add_co_u32_e32 v78, vcc, s38, v72
	v_pk_fma_f32 v[4:5], v[4:5], v[80:81], v[88:89]
	s_nop 0
	v_addc_co_u32_e32 v79, vcc, -1, v73, vcc
	global_store_dwordx4 v[78:79], v[2:5], off offset:-3072
	s_nop 1
	v_mov_b64_e32 v[2:3], v[184:185]
	v_mov_b64_e32 v[4:5], v[186:187]
	s_nop 0
	s_nop 1
	v_mov_b64_e32 v[86:87], v[216:217]
	v_mov_b64_e32 v[88:89], v[218:219]
	s_waitcnt vmcnt(0)
	v_pk_fma_f32 v[2:3], v[2:3], v[66:67], v[86:87]
	v_pk_fma_f32 v[4:5], v[4:5], v[70:71], v[88:89]
	global_store_dwordx4 v[78:79], v[2:5], off offset:-2048
	s_nop 1
	v_mov_b64_e32 v[2:3], v[188:189]
	v_mov_b64_e32 v[4:5], v[190:191]
	s_nop 1
	v_mov_b64_e32 v[86:87], v[220:221]
	v_mov_b64_e32 v[88:89], v[222:223]
	v_pk_mul_f32 v[66:67], v[68:69], v[10:11] op_sel_hi:[1,0]
	s_waitcnt vmcnt(0)
	v_pk_fma_f32 v[2:3], v[2:3], v[62:63], v[86:87]
	v_pk_fma_f32 v[4:5], v[4:5], v[66:67], v[88:89]
	global_store_dwordx4 v[78:79], v[2:5], off offset:-1024
	s_nop 1
	v_mov_b64_e32 v[2:3], v[192:193]
	v_mov_b64_e32 v[4:5], v[194:195]
	s_nop 0
	s_nop 1
	v_mov_b64_e32 v[66:67], v[236:237]
	v_mov_b64_e32 v[68:69], v[238:239]
	v_add_co_u32_e32 v62, vcc, s82, v76
	s_waitcnt vmcnt(0)
	v_pk_fma_f32 v[2:3], v[2:3], v[58:59], v[66:67]
	v_pk_fma_f32 v[4:5], v[4:5], v[60:61], v[68:69]
	v_addc_co_u32_e32 v63, vcc, 0, v77, vcc
	global_store_dwordx4 v[72:73], v[2:5], off offset:-4096
	v_add_co_u32_e32 v66, vcc, s82, v74
	s_nop 1
	v_mov_b64_e32 v[2:3], v[196:197]
	v_mov_b64_e32 v[4:5], v[198:199]
	s_nop 0
	v_addc_co_u32_e32 v67, vcc, 0, v75, vcc
	s_nop 1
	v_mov_b64_e32 v[58:59], v[240:241]
	v_mov_b64_e32 v[60:61], v[242:243]
	s_waitcnt vmcnt(0)
	v_pk_fma_f32 v[2:3], v[2:3], v[48:49], v[58:59]
	v_pk_fma_f32 v[4:5], v[4:5], v[52:53], v[60:61]
	global_store_dwordx4 v[72:73], v[2:5], off offset:-3072
	s_nop 1
	v_mov_b64_e32 v[2:3], v[200:201]
	v_mov_b64_e32 v[4:5], v[202:203]
	s_nop 0
	s_nop 1
	v_mov_b64_e32 v[58:59], v[128:129]
	v_mov_b64_e32 v[60:61], v[130:131]
	v_pk_mul_f32 v[48:49], v[64:65], v[10:11] op_sel_hi:[1,0]
	v_pk_mul_f32 v[52:53], v[56:57], v[10:11] op_sel_hi:[1,0]
	s_waitcnt vmcnt(0)
	v_pk_fma_f32 v[4:5], v[4:5], v[48:49], v[60:61]
	v_pk_fma_f32 v[2:3], v[2:3], v[52:53], v[58:59]
	global_store_dwordx4 v[72:73], v[2:5], off offset:-2048
	s_nop 1
	v_mov_b64_e32 v[2:3], v[204:205]
	v_mov_b64_e32 v[4:5], v[206:207]
	s_nop 1
	v_mov_b64_e32 v[56:57], v[132:133]
	v_mov_b64_e32 v[58:59], v[134:135]
	s_waitcnt vmcnt(0)
	v_pk_fma_f32 v[2:3], v[2:3], v[40:41], v[56:57]
	v_pk_fma_f32 v[4:5], v[4:5], v[46:47], v[58:59]
	global_store_dwordx4 v[72:73], v[2:5], off offset:-1024
	s_nop 1
	v_mov_b64_e32 v[2:3], v[208:209]
	v_mov_b64_e32 v[4:5], v[210:211]
	s_nop 0
	s_nop 1
	v_mov_b64_e32 v[46:47], v[140:141]
	v_mov_b64_e32 v[48:49], v[142:143]
	v_pk_mul_f32 v[40:41], v[42:43], v[10:11] op_sel_hi:[1,0]
	v_and_b32_e32 v43, 0xffff0000, v31
	v_and_b32_e32 v42, 0xffff0000, v30
	v_add_f32_e32 v10, v16, v17
	s_waitcnt vmcnt(0)
	v_pk_fma_f32 v[2:3], v[38:39], v[2:3], v[46:47]
	v_pk_fma_f32 v[4:5], v[40:41], v[4:5], v[48:49]
	v_lshlrev_b32_e32 v38, 16, v34
	v_lshlrev_b32_e32 v39, 16, v36
	v_and_b32_e32 v47, 0xffff0000, v36
	v_and_b32_e32 v46, 0xffff0000, v34
	v_and_b32_e32 v49, 0xffff0000, v37
	v_and_b32_e32 v48, 0xffff0000, v35
	global_store_dwordx4 v[72:73], v[2:5], off
	v_and_b32_e32 v41, 0xffff0000, v33
	v_and_b32_e32 v40, 0xffff0000, v32
	v_pk_add_f32 v[2:3], v[38:39], v[46:47]
	v_pk_add_f32 v[4:5], v[44:45], v[48:49]
	s_nop 0
	v_pk_add_f32 v[2:3], v[2:3], v[4:5]
	v_lshlrev_b32_e32 v5, 16, v33
	v_add_f32_e32 v2, 0, v2
	v_lshlrev_b32_e32 v4, 16, v32
	v_add_f32_e32 v20, v2, v3
	v_pk_add_f32 v[2:3], v[4:5], v[40:41]
	v_pk_add_f32 v[32:33], v[24:25], v[22:23]
	v_pk_add_f32 v[2:3], v[2:3], v[2:3] op_sel:[0,1] op_sel_hi:[1,0]
	s_nop 0
	v_mov_b32_e32 v3, v19
	v_pk_add_f32 v[2:3], v[20:21], v[2:3]
	s_nop 0
	v_pk_add_f32 v[32:33], v[2:3], v[32:33]
	v_lshlrev_b32_e32 v3, 16, v31
	v_lshlrev_b32_e32 v2, 16, v30
	v_pk_add_f32 v[30:31], v[2:3], v[42:43]
	v_pk_add_f32 v[32:33], v[32:33], v[32:33] op_sel:[0,1] op_sel_hi:[1,0]
	v_pk_add_f32 v[30:31], v[30:31], v[30:31] op_sel:[0,1] op_sel_hi:[1,0]
	v_mov_b32_e32 v33, v8
	v_mov_b32_e32 v31, v9
	v_pk_add_f32 v[30:31], v[32:33], v[30:31]
	v_pk_add_f32 v[32:33], v[12:13], v[10:11]
	s_nop 0
	v_pk_add_f32 v[30:31], v[30:31], v[32:33]
	s_nop 0
	v_add_f32_e32 v10, v30, v31
	ds_bpermute_b32 v12, v7, v10
	s_waitcnt lgkmcnt(0)
	v_add_f32_e32 v10, v10, v12
	ds_bpermute_b32 v12, v18, v10
	s_waitcnt lgkmcnt(0)
	v_add_f32_e32 v10, v10, v12
	ds_bpermute_b32 v12, v50, v10
	s_waitcnt lgkmcnt(0)
	v_add_f32_e32 v10, v10, v12
	ds_bpermute_b32 v12, v54, v10
	s_waitcnt lgkmcnt(0)
	v_add_f32_e32 v10, v10, v12
	ds_bpermute_b32 v12, v82, v10
	s_waitcnt lgkmcnt(0)
	v_add_f32_e32 v10, v10, v12
	ds_bpermute_b32 v12, v84, v10
	s_waitcnt lgkmcnt(0)
	v_add_f32_e32 v12, v10, v12
	v_fmac_f32_e32 v48, 0xba000000, v12
	v_fmac_f32_e32 v46, 0xba000000, v12
	v_fmac_f32_e32 v49, 0xba000000, v12
	v_fmac_f32_e32 v47, 0xba000000, v12
	v_fmac_f32_e32 v44, 0xba000000, v12
	v_fmac_f32_e32 v38, 0xba000000, v12
	v_fmac_f32_e32 v45, 0xba000000, v12
	v_fmac_f32_e32 v39, 0xba000000, v12
	v_mov_b32_e32 v31, v47
	v_mov_b32_e32 v35, v46
	v_pk_mul_f32 v[32:33], v[46:47], v[46:47]
	v_pk_mul_f32 v[46:47], v[48:49], v[48:49]
	v_mov_b32_e32 v30, v39
	v_mov_b32_e32 v34, v38
	v_pk_fma_f32 v[38:39], v[38:39], v[38:39], v[32:33]
	v_mov_b32_e32 v32, v45
	v_mov_b32_e32 v36, v44
	v_pk_fma_f32 v[44:45], v[44:45], v[44:45], v[46:47]
	v_fmac_f32_e32 v40, 0xba000000, v12
	v_pk_add_f32 v[38:39], v[38:39], v[44:45]
	v_fmac_f32_e32 v41, 0xba000000, v12
	v_fmac_f32_e32 v5, 0xba000000, v12
	v_pk_add_f32 v[44:45], v[38:39], v[38:39] op_sel_hi:[0,1]
	v_fmac_f32_e32 v4, 0xba000000, v12
	v_mov_b32_e32 v38, v5
	v_mov_b32_e32 v39, v41
	v_mov_b32_e32 v5, v40
	v_pk_mul_f32 v[46:47], v[38:39], v[38:39]
	v_pk_mul_f32 v[40:41], v[4:5], v[4:5]
	v_fmac_f32_e32 v26, 0xba000000, v12
	v_mov_b32_e32 v33, v49
	v_mov_b32_e32 v37, v48
	v_pk_mov_b32 v[48:49], v[40:41], v[46:47] op_sel:[1,0]
	v_mov_b32_e32 v41, v47
	v_fmac_f32_e32 v27, 0xba000000, v12
	v_fmac_f32_e32 v28, 0xba000000, v12
	v_mul_f32_e32 v10, v26, v26
	v_pk_add_f32 v[40:41], v[48:49], v[40:41]
	v_fmac_f32_e32 v29, 0xba000000, v12
	v_pk_fma_f32 v[46:47], v[26:27], v[26:27], v[10:11] op_sel_hi:[1,1,0]
	v_mul_f32_e32 v10, v28, v28
	v_pk_add_f32 v[40:41], v[40:41], v[40:41] op_sel_hi:[0,1]
	v_pk_fma_f32 v[48:49], v[28:29], v[28:29], v[10:11] op_sel_hi:[1,1,0]
	v_fmac_f32_e32 v23, 0xba000000, v12
	v_fmac_f32_e32 v25, 0xba000000, v12
	v_fmac_f32_e32 v19, 0xba000000, v12
	v_fmac_f32_e32 v21, 0xba000000, v12
	v_mul_f32_e32 v46, v21, v21
	v_mul_f32_e32 v48, v19, v19
	v_mul_f32_e32 v40, v25, v25
	v_mul_f32_e32 v44, v23, v23
	v_pk_add_f32 v[46:47], v[46:47], v[48:49]
	v_pk_add_f32 v[40:41], v[40:41], v[44:45]
	v_fmac_f32_e32 v42, 0xba000000, v12
	v_pk_add_f32 v[40:41], v[46:47], v[40:41]
	v_fmac_f32_e32 v43, 0xba000000, v12
	v_fmac_f32_e32 v3, 0xba000000, v12
	v_pk_add_f32 v[44:45], v[40:41], v[40:41] op_sel_hi:[0,1]
	v_fmac_f32_e32 v2, 0xba000000, v12
	v_mov_b32_e32 v40, v3
	v_mov_b32_e32 v41, v43
	v_mov_b32_e32 v3, v42
	v_pk_mul_f32 v[46:47], v[40:41], v[40:41]
	v_pk_mul_f32 v[42:43], v[2:3], v[2:3]
	v_fmac_f32_e32 v14, 0xba000000, v12
	v_pk_mov_b32 v[48:49], v[42:43], v[46:47] op_sel:[1,0]
	v_mov_b32_e32 v43, v47
	v_fmac_f32_e32 v15, 0xba000000, v12
	v_fmac_f32_e32 v16, 0xba000000, v12
	v_mul_f32_e32 v10, v14, v14
	v_pk_add_f32 v[42:43], v[48:49], v[42:43]
	v_fmac_f32_e32 v17, 0xba000000, v12
	v_pk_fma_f32 v[46:47], v[14:15], v[14:15], v[10:11] op_sel_hi:[1,1,0]
	v_mul_f32_e32 v10, v16, v16
	v_pk_add_f32 v[42:43], v[42:43], v[42:43] op_sel_hi:[0,1]
	v_pk_fma_f32 v[48:49], v[16:17], v[16:17], v[10:11] op_sel_hi:[1,1,0]
	v_fmac_f32_e32 v11, 0xba000000, v12
	v_fmac_f32_e32 v13, 0xba000000, v12
	v_fmac_f32_e32 v9, 0xba000000, v12
	v_fmac_f32_e32 v8, 0xba000000, v12
	v_mul_f32_e32 v46, v8, v8
	v_mul_f32_e32 v48, v9, v9
	v_mul_f32_e32 v42, v13, v13
	v_mul_f32_e32 v44, v11, v11
	v_pk_add_f32 v[46:47], v[46:47], v[48:49]
	v_pk_add_f32 v[42:43], v[42:43], v[44:45]
	s_nop 0
	v_pk_add_f32 v[42:43], v[46:47], v[42:43]
	s_nop 0
	v_add_f32_e32 v10, v42, v43
	ds_bpermute_b32 v7, v7, v10
	v_lshlrev_b32_e32 v42, 2, v1
	v_ashrrev_i32_e32 v43, 31, v42
	s_waitcnt lgkmcnt(0)
	v_add_f32_e32 v7, v10, v7
	ds_bpermute_b32 v10, v18, v7
	s_waitcnt lgkmcnt(0)
	v_add_f32_e32 v7, v7, v10
	ds_bpermute_b32 v10, v50, v7
	s_waitcnt lgkmcnt(0)
	v_add_f32_e32 v7, v7, v10
	ds_bpermute_b32 v10, v54, v7
	v_lshlrev_b64 v[54:55], 2, v[42:43]
	v_lshl_add_u64 v[44:45], s[20:21], 0, v[54:55]
	v_lshl_add_u64 v[42:43], s[18:19], 0, v[54:55]
	s_nop 1
	v_mov_b64_e32 v[46:47], v[180:181]
	v_mov_b64_e32 v[48:49], v[182:183]
	s_nop 1
	v_mov_b64_e32 v[50:51], v[212:213]
	v_mov_b64_e32 v[52:53], v[214:215]
	s_waitcnt lgkmcnt(0)
	v_add_f32_e32 v7, v7, v10
	ds_bpermute_b32 v10, v82, v7
	s_waitcnt lgkmcnt(0)
	v_add_f32_e32 v7, v7, v10
	ds_bpermute_b32 v10, v84, v7
	s_waitcnt lgkmcnt(0)
	v_add_f32_e32 v7, v7, v10
	v_fmamk_f32 v7, v7, 0x3a000000, v250
	v_cmp_gt_f32_e32 vcc, s96, v7
	v_mul_f32_e32 v10, 0x4f800000, v7
	s_nop 0
	v_cndmask_b32_e32 v7, v7, v10, vcc
	v_sqrt_f32_e32 v10, v7
	s_nop 0
	v_add_u32_e32 v12, -1, v10
	v_fma_f32 v18, -v12, v10, v7
	v_cmp_ge_f32_e64 s[10:11], 0, v18
	v_add_u32_e32 v18, 1, v10
	s_nop 0
	v_cndmask_b32_e64 v12, v10, v12, s[10:11]
	v_fma_f32 v10, -v18, v10, v7
	v_cmp_lt_f32_e64 s[10:11], 0, v10
	s_nop 1
	v_cndmask_b32_e64 v10, v12, v18, s[10:11]
	v_mul_f32_e32 v12, 0x37800000, v10
	v_cndmask_b32_e32 v10, v10, v12, vcc
	v_cmp_class_f32_e32 vcc, v7, v251
	s_nop 1
	v_cndmask_b32_e32 v7, v10, v7, vcc
	v_div_scale_f32 v10, s[10:11], v7, v7, 1.0
	v_rcp_f32_e32 v12, v10
	s_nop 0
	v_fma_f32 v18, -v10, v12, 1.0
	v_fmac_f32_e32 v12, v18, v12
	v_div_scale_f32 v18, vcc, 1.0, v7, 1.0
	v_mul_f32_e32 v20, v18, v12
	v_fma_f32 v22, -v10, v20, v18
	v_fmac_f32_e32 v20, v22, v12
	v_fma_f32 v10, -v10, v20, v18
	v_div_fmas_f32 v10, v10, v12, v20
	v_div_fixup_f32 v12, v10, v7, 1.0
	v_pk_mul_f32 v[36:37], v[36:37], v[12:13] op_sel_hi:[1,0]
	v_pk_mul_f32 v[34:35], v[34:35], v[12:13] op_sel_hi:[1,0]
	v_pk_mul_f32 v[32:33], v[32:33], v[12:13] op_sel_hi:[1,0]
	v_pk_mul_f32 v[30:31], v[30:31], v[12:13] op_sel_hi:[1,0]
	v_pk_mul_f32 v[38:39], v[38:39], v[12:13] op_sel_hi:[1,0]
	v_pk_mul_f32 v[4:5], v[4:5], v[12:13] op_sel_hi:[1,0]
	v_pk_mul_f32 v[26:27], v[26:27], v[12:13] op_sel_hi:[1,0]
	v_mov_b32_e32 v18, v21
	v_mov_b32_e32 v22, v25
	v_pk_mul_f32 v[18:19], v[18:19], v[12:13] op_sel_hi:[1,0]
	v_pk_mul_f32 v[2:3], v[2:3], v[12:13] op_sel_hi:[1,0]
	v_pk_mul_f32 v[16:17], v[16:17], v[12:13] op_sel_hi:[1,0]
	v_pk_mul_f32 v[14:15], v[14:15], v[12:13] op_sel_hi:[1,0]
	v_mov_b32_e32 v10, v13
	v_pk_mul_f32 v[10:11], v[10:11], v[12:13] op_sel_hi:[1,0]
	v_pk_mul_f32 v[8:9], v[8:9], v[12:13] op_sel_hi:[1,0]
	s_waitcnt vmcnt(0)
	v_pk_fma_f32 v[34:35], v[46:47], v[34:35], v[50:51]
	v_pk_fma_f32 v[36:37], v[48:49], v[36:37], v[52:53]
	v_lshl_add_u64 v[50:51], s[22:23], 0, v[54:55]
	global_store_dwordx4 v[50:51], v[34:37], off
	s_nop 1
	v_mov_b64_e32 v[34:35], v[184:185]
	v_mov_b64_e32 v[36:37], v[186:187]
	s_nop 0
	s_nop 1
	v_mov_b64_e32 v[46:47], v[216:217]
	v_mov_b64_e32 v[48:49], v[218:219]
	s_waitcnt vmcnt(0)
	v_pk_fma_f32 v[30:31], v[34:35], v[30:31], v[46:47]
	v_pk_fma_f32 v[32:33], v[36:37], v[32:33], v[48:49]
	global_store_dwordx4 v[50:51], v[30:33], off offset:1024
	s_nop 1
	v_mov_b64_e32 v[30:31], v[188:189]
	v_mov_b64_e32 v[32:33], v[190:191]
	s_nop 1
	v_mov_b64_e32 v[34:35], v[220:221]
	v_mov_b64_e32 v[36:37], v[222:223]
	s_waitcnt vmcnt(0)
	v_pk_fma_f32 v[30:31], v[30:31], v[4:5], v[34:35]
	v_pk_fma_f32 v[32:33], v[32:33], v[38:39], v[36:37]
	global_store_dwordx4 v[50:51], v[30:33], off offset:2048
	s_nop 1
	v_mov_b64_e32 v[30:31], v[192:193]
	v_mov_b64_e32 v[32:33], v[194:195]
	s_nop 0
	s_nop 1
	v_mov_b64_e32 v[34:35], v[236:237]
	v_mov_b64_e32 v[36:37], v[238:239]
	v_pk_mul_f32 v[4:5], v[28:29], v[12:13] op_sel_hi:[1,0]
	s_waitcnt vmcnt(0)
	v_pk_fma_f32 v[26:27], v[30:31], v[26:27], v[34:35]
	v_add_co_u32_e32 v34, vcc, s82, v44
	v_pk_fma_f32 v[28:29], v[32:33], v[4:5], v[36:37]
	s_nop 0
	v_addc_co_u32_e32 v35, vcc, 0, v45, vcc
	global_store_dwordx4 v[50:51], v[26:29], off offset:3072
	v_add_co_u32_e32 v36, vcc, s82, v42
	s_nop 1
	v_mov_b64_e32 v[26:27], v[196:197]
	v_mov_b64_e32 v[28:29], v[198:199]
	s_nop 0
	v_addc_co_u32_e32 v37, vcc, 0, v43, vcc
	s_nop 1
	v_mov_b64_e32 v[30:31], v[240:241]
	v_mov_b64_e32 v[32:33], v[242:243]
	v_pk_mul_f32 v[4:5], v[22:23], v[12:13] op_sel_hi:[1,0]
	s_waitcnt vmcnt(0)
	v_pk_fma_f32 v[18:19], v[26:27], v[18:19], v[30:31]
	v_add_co_u32_e32 v26, vcc, s82, v50
	v_pk_fma_f32 v[20:21], v[28:29], v[4:5], v[32:33]
	s_nop 0
	v_addc_co_u32_e32 v27, vcc, 0, v51, vcc
	global_store_dwordx4 v[26:27], v[18:21], off
	s_nop 1
	v_mov_b64_e32 v[18:19], v[200:201]
	v_mov_b64_e32 v[20:21], v[202:203]
	s_nop 0
	s_nop 1
	v_mov_b64_e32 v[22:23], v[128:129]
	v_mov_b64_e32 v[24:25], v[130:131]
	v_pk_mul_f32 v[4:5], v[40:41], v[12:13] op_sel_hi:[1,0]
	s_waitcnt vmcnt(0)
	v_pk_fma_f32 v[2:3], v[18:19], v[2:3], v[22:23]
	v_pk_fma_f32 v[4:5], v[20:21], v[4:5], v[24:25]
	global_store_dwordx4 v[26:27], v[2:5], off offset:1024
	s_nop 1
	v_mov_b64_e32 v[2:3], v[204:205]
	v_mov_b64_e32 v[4:5], v[206:207]
	s_nop 1
	v_mov_b64_e32 v[18:19], v[132:133]
	v_mov_b64_e32 v[20:21], v[134:135]
	s_waitcnt vmcnt(0)
	v_pk_fma_f32 v[2:3], v[2:3], v[14:15], v[18:19]
	v_pk_fma_f32 v[4:5], v[4:5], v[16:17], v[20:21]
	global_store_dwordx4 v[26:27], v[2:5], off offset:2048
	s_nop 1
	v_mov_b64_e32 v[2:3], v[208:209]
	v_mov_b64_e32 v[4:5], v[210:211]
	s_nop 0
	s_nop 1
	v_mov_b64_e32 v[14:15], v[140:141]
	v_mov_b64_e32 v[16:17], v[142:143]
	s_waitcnt vmcnt(0)
	v_pk_fma_f32 v[2:3], v[8:9], v[2:3], v[14:15]
	v_pk_fma_f32 v[4:5], v[10:11], v[4:5], v[16:17]
	global_store_dwordx4 v[26:27], v[2:5], off offset:3072
	s_cbranch_scc1 .LBB0_1705
